# static seeding of the XCD-local GEMM queues in phases A and F (first tile = blockIdx>>3, atomics offset by per-shard block count)
# speedup vs baseline: 1.0234x; 1.0047x over previous
.LBB0_119:
	s_add_i32 s0, s11, s29
	s_and_b32 s14, s0, 7
	s_or_b32 s0, s14, s9
	s_ashr_i32 s1, s0, 31
	s_lshl_b64 s[0:1], s[0:1], 7
	v_readlane_b32 s2, v253, 47
	s_add_u32 s2, s2, s0
	v_readlane_b32 s0, v253, 48
	s_addc_u32 s3, s0, s1
	s_barrier
	s_and_saveexec_b64 s[0:1], s[12:13]
	s_cbranch_execz .LBB0_123
	s_cmp_lg_u32 s11, 0
	s_cbranch_scc1 .Lfseed_atomic
	v_readlane_b32 s4, v254, 20
	s_lshr_b32 s4, s4, 3
	v_mov_b32_e32 v1, s4
	ds_write_b32 v161, v1
	s_branch .LBB0_123
.Lfseed_atomic:
	v_readlane_b32 s98, v255, 13
	s_sub_i32 s98, s98, s14
	s_add_i32 s98, s98, 7
	s_lshr_b32 s98, s98, 3
	s_mov_b64 s[6:7], exec
	v_mbcnt_lo_u32_b32 v1, s6, 0
	v_mbcnt_hi_u32_b32 v1, s7, v1
	v_cmp_eq_u32_e32 vcc, 0, v1
	s_and_saveexec_b64 s[4:5], vcc
	s_cbranch_execz .LBB0_122
	s_bcnt1_i32_b64 s6, s[6:7]
	s_waitcnt vmcnt(0)
	v_mov_b32_e32 v2, s6
	global_atomic_add v2, v131, v2, s[2:3] sc0
.LBB0_122:
	s_or_b64 exec, exec, s[4:5]
	s_waitcnt vmcnt(0)
	v_readfirstlane_b32 s4, v2
	s_nop 1
	v_add_u32_e32 v1, s4, v1
	v_add_u32_e32 v1, s98, v1
	ds_write_b32 v161, v1

.LBB0_125:
	s_or_b64 exec, exec, s[4:5]
	s_waitcnt vmcnt(0)
	v_readfirstlane_b32 s4, v2
	s_nop 1
	v_add_u32_e32 v1, s4, v1
	s_add_i32 s98, s11, s29
	s_and_b32 s98, s98, 7
	v_readlane_b32 s99, v255, 13
	s_sub_i32 s99, s99, s98
	s_add_i32 s99, s99, 7
	s_lshr_b32 s99, s99, 3
	v_add_u32_e32 v1, s99, v1
	ds_write_b32 v161, v1

.LBB0_744:
	s_add_i32 s2, s15, s29
	s_and_b32 s18, s2, 7
	s_or_b32 s2, s18, s14
	s_ashr_i32 s3, s2, 31
	s_lshl_b64 s[2:3], s[2:3], 7
	v_readlane_b32 s4, v253, 47
	s_add_u32 s2, s4, s2
	v_readlane_b32 s4, v253, 48
	s_addc_u32 s3, s4, s3
	s_barrier
	s_and_saveexec_b64 s[4:5], s[12:13]
	s_cbranch_execz .LBB0_748
	s_cmp_lg_u32 s15, 0
	s_cbranch_scc1 .Laseed_atomic
	v_readlane_b32 s6, v254, 20
	s_lshr_b32 s6, s6, 3
	v_mov_b32_e32 v1, s6
	ds_write_b32 v161, v1
	s_branch .LBB0_748
.Laseed_atomic:
	v_readlane_b32 s98, v255, 13
	s_sub_i32 s98, s98, s18
	s_add_i32 s98, s98, 7
	s_lshr_b32 s98, s98, 3
	s_mov_b64 s[8:9], exec
	v_mbcnt_lo_u32_b32 v1, s8, 0
	v_mbcnt_hi_u32_b32 v1, s9, v1
	v_cmp_eq_u32_e32 vcc, 0, v1
	s_and_saveexec_b64 s[6:7], vcc
	s_cbranch_execz .LBB0_747
	s_bcnt1_i32_b64 s8, s[8:9]
	s_waitcnt vmcnt(0)
	v_mov_b32_e32 v2, s8
	global_atomic_add v2, v131, v2, s[2:3] sc0
.LBB0_747:
	s_or_b64 exec, exec, s[6:7]
	s_waitcnt vmcnt(0)
	v_readfirstlane_b32 s6, v2
	s_nop 1
	v_add_u32_e32 v1, s6, v1
	v_add_u32_e32 v1, s98, v1
	ds_write_b32 v161, v1

.LBB0_750:
	s_or_b64 exec, exec, s[6:7]
	s_waitcnt vmcnt(0)
	v_readfirstlane_b32 s6, v2
	s_nop 1
	v_add_u32_e32 v1, s6, v1
	s_add_i32 s98, s15, s29
	s_and_b32 s98, s98, 7
	v_readlane_b32 s99, v255, 13
	s_sub_i32 s99, s99, s98
	s_add_i32 s99, s99, 7
	s_lshr_b32 s99, s99, 3
	v_add_u32_e32 v1, s99, v1
	ds_write_b32 v161, v1
